# combined: MLA prefetch issue inside QK gaps + NSA P.V-gap row sums + MLA K/V staging before P.V, on top of v6
# speedup vs baseline: 1.0033x; 1.0033x over previous
; template <int D, int DV, int MODE, bool HASBIAS, bool JOINT, bool DEFER, class KA, class VA, class PF, class BF, class VF, class NM, class WS, class CB> ...
;     ...
;     for (int t = 0; t < nt; t += 2) {
;         if (t + 2 < nt) FA_LOAD(t + 2, kregA, vregA, pregA);
;         compute(t, 0);
.LBB0_1002:
	s_add_i32 s52, s54, 2
	s_add_i32 s53, s48, -1
	s_cmp_lt_u32 s53, s38
	s_cselect_b64 s[0:1], -1, 0
	s_add_i32 s10, s49, 0xffffff81
	s_add_i32 s11, s49, 0xffffffa1
	s_max_i32 s10, s10, s11
	s_cmp_gt_i32 s10, s39
	s_cbranch_scc0 .LBB0_1016
	s_cmp_ge_u32 s53, s38
	s_cbranch_scc1 .LBB0_1016
	s_lshl_b32 s74, s52, 6
	s_and_saveexec_b64 s[8:9], s[40:41]
	s_cbranch_execz .LBB0_1009
	s_and_saveexec_b64 s[10:11], s[44:45]
	s_xor_b64 s[10:11], exec, s[10:11]
	v_lshl_add_u64 v[36:37], v[136:137], 0, s[74:75]
	v_lshlrev_b64 v[36:37], 6, v[36:37]
	v_lshl_add_u64 v[36:37], v[140:141], 0, v[36:37]
	s_mov_b64 s[12:13], 0x340fff80
	v_lshl_add_u64 v[36:37], v[36:37], 0, s[12:13]
	s_andn2_saveexec_b64 s[10:11], s[10:11]
	v_lshl_add_u64 v[36:37], s[20:21], 0, v[146:147]
	s_mov_b64 s[12:13], 0x24120000
	v_lshl_add_u64 v[36:37], v[36:37], 0, s[12:13]
	s_or_b64 exec, exec, s[10:11]
	global_load_dwordx4 v[108:111], v[36:37], off

; #define LAS __attribute__((address_space(3)))
; template <int DK16>
; __device__ __forceinline__ f32x16 qk_sub(const LAS unsigned char* Kt, int ks, int sub, const bf16x8 (&qf)[DK16], int r32, int hi) {
;     f32x16 s;
; #pragma unroll
;     for (int v = 0; v < 16; ++v) s[v] = 0.f;
;     const LAS unsigned char* p = Kt + (sub * 32 + r32) * ks + hi * 16;
; #pragma unroll
;     for (int dk = 0; dk < DK16; ++dk) { const bf16x8 kf = *(const LAS bf16x8*)(p + dk * 32); s = __builtin_amdgcn_mfma_f32_32x32x16_bf16(kf, qf[dk], s, 0, 0, 0); }
;     return s;
; }
.LBB0_1016:
	s_add_i32 s10, s49, 0xffffff81
	s_cmp_le_i32 s10, s39
	s_cselect_b64 s[8:9], -1, 0
	s_add_i32 s11, s49, 0xffffffa1
	s_cmp_le_i32 s11, s39
	s_cselect_b64 s[18:19], -1, 0
	s_max_i32 s10, s10, s11
	s_cmp_gt_i32 s10, s39
	s_cselect_b64 s[10:11], -1, 0
	s_andn2_b64 vcc, exec, s[10:11]
	s_cbranch_vccz .LBB0_1027
	v_add_u32_e32 v1, v173, v2
	ds_read_b128 v[36:39], v1
	ds_read_b128 v[52:55], v1 offset:32
	s_cmp_ge_u32 s53, s38
	s_cbranch_scc1 .Lmla_qkp1
	s_lshl_b32 s74, s52, 6
	s_mov_b64 s[12:13], 0x340fff80
	s_mov_b64 s[100:101], 0x24120000
	s_add_i32 s10, s49, 0xffffffa0
	s_sub_i32 s11, s49, 64
	s_max_i32 s10, s10, s11
	s_cmp_le_i32 s10, s30
	s_cselect_b64 s[16:17], -1, 0
	s_and_b64 vcc, exec, s[16:17]
	s_waitcnt lgkmcnt(0)
	v_mfma_f32_32x32x16_bf16 v[36:51], v[36:39], v[84:87], 0
	ds_read_b128 v[68:71], v1 offset:6688
	v_lshl_add_u64 v[72:73], v[136:137], 0, s[74:75]
	v_lshlrev_b64 v[72:73], 6, v[72:73]
	v_lshl_add_u64 v[72:73], v[140:141], 0, v[72:73]
	v_lshl_add_u64 v[72:73], v[72:73], 0, s[12:13]
	v_mfma_f32_32x32x16_bf16 v[36:51], v[52:55], v[88:91], v[36:51]
	ds_read_b128 v[52:55], v1 offset:64
	v_lshl_add_u64 v[74:75], s[20:21], 0, v[146:147]
	v_lshl_add_u64 v[74:75], v[74:75], 0, s[100:101]
	v_cndmask_b32_e64 v72, v74, v72, s[44:45]
	v_cndmask_b32_e64 v73, v75, v73, s[44:45]
	s_waitcnt lgkmcnt(0)
	v_mfma_f32_32x32x16_bf16 v[36:51], v[52:55], v[92:95], v[36:51]
	global_load_dwordx4 v[108:111], v[72:73], off
	ds_read_b128 v[52:55], v1 offset:96
	v_lshl_add_u64 v[72:73], v[138:139], 0, s[74:75]
	v_lshlrev_b64 v[72:73], 6, v[72:73]
	v_lshl_add_u64 v[72:73], v[142:143], 0, v[72:73]
	v_lshl_add_u64 v[72:73], v[72:73], 0, s[12:13]
	s_waitcnt lgkmcnt(0)
	v_mfma_f32_32x32x16_bf16 v[36:51], v[52:55], v[96:99], v[36:51]
	ds_read_b128 v[52:55], v1 offset:128
	v_lshl_add_u64 v[74:75], s[20:21], 0, v[148:149]
	v_lshl_add_u64 v[74:75], v[74:75], 0, s[100:101]
	v_cndmask_b32_e64 v72, v74, v72, s[46:47]
	v_cndmask_b32_e64 v73, v75, v73, s[46:47]
	s_waitcnt lgkmcnt(0)
	v_mfma_f32_32x32x16_bf16 v[36:51], v[52:55], v[100:103], v[36:51]
	ds_read_b128 v[52:55], v1 offset:160
	s_cmp_eq_u64 s[42:43], 0
	s_cbranch_scc1 .Lmla_c2s1
	global_load_dwordx4 v[112:115], v[72:73], off
.Lmla_c2s1:
	v_lshl_add_u64 v[74:75], s[20:21], 0, v[144:145]
	s_mov_b64 s[12:13], 0x28100000
	v_lshl_add_u64 v[74:75], v[74:75], 0, s[12:13]
	s_waitcnt lgkmcnt(0)
	v_mfma_f32_32x32x16_bf16 v[36:51], v[52:55], v[104:107], v[36:51]
	global_load_dwordx4 v[116:119], v[74:75], off offset:256
	ds_read_b128 v[52:55], v1 offset:6656
	s_waitcnt lgkmcnt(0)
	v_mfma_f32_32x32x16_bf16 v[52:67], v[52:55], v[84:87], 0
	v_mfma_f32_32x32x16_bf16 v[52:67], v[68:71], v[88:91], v[52:67]
	ds_read_b128 v[68:71], v1 offset:6720
	s_waitcnt lgkmcnt(0)
	v_mfma_f32_32x32x16_bf16 v[52:67], v[68:71], v[92:95], v[52:67]
	ds_read_b128 v[68:71], v1 offset:6752
	s_waitcnt lgkmcnt(0)
	v_mfma_f32_32x32x16_bf16 v[52:67], v[68:71], v[96:99], v[52:67]
	ds_read_b128 v[68:71], v1 offset:6784
	s_waitcnt lgkmcnt(0)
	v_mfma_f32_32x32x16_bf16 v[52:67], v[68:71], v[100:103], v[52:67]
	ds_read_b128 v[68:71], v1 offset:6816
	s_waitcnt lgkmcnt(0)
	v_mfma_f32_32x32x16_bf16 v[52:67], v[68:71], v[104:107], v[52:67]
	s_cbranch_vccnz .LBB0_1019
	s_branch .Lmla_m1
.Lmla_qkp1:
	s_add_i32 s10, s49, 0xffffffa0
	s_sub_i32 s11, s49, 64
	s_max_i32 s10, s10, s11
	s_waitcnt lgkmcnt(0)
	v_mfma_f32_32x32x16_bf16 v[36:51], v[36:39], v[84:87], 0
	s_cmp_le_i32 s10, s30
	s_cselect_b64 s[16:17], -1, 0
	s_and_b64 vcc, exec, s[16:17]
	ds_read_b128 v[68:71], v1 offset:6688
	v_mfma_f32_32x32x16_bf16 v[36:51], v[52:55], v[88:91], v[36:51]
	ds_read_b128 v[52:55], v1 offset:64
	s_waitcnt lgkmcnt(0)
	v_mfma_f32_32x32x16_bf16 v[36:51], v[52:55], v[92:95], v[36:51]
	ds_read_b128 v[52:55], v1 offset:96
	s_waitcnt lgkmcnt(0)
	v_mfma_f32_32x32x16_bf16 v[36:51], v[52:55], v[96:99], v[36:51]
	ds_read_b128 v[52:55], v1 offset:128
	s_waitcnt lgkmcnt(0)
	v_mfma_f32_32x32x16_bf16 v[36:51], v[52:55], v[100:103], v[36:51]
	ds_read_b128 v[52:55], v1 offset:160
	s_waitcnt lgkmcnt(0)
	v_mfma_f32_32x32x16_bf16 v[36:51], v[52:55], v[104:107], v[36:51]
	ds_read_b128 v[52:55], v1 offset:6656
	s_waitcnt lgkmcnt(0)
	v_mfma_f32_32x32x16_bf16 v[52:67], v[52:55], v[84:87], 0
	v_mfma_f32_32x32x16_bf16 v[52:67], v[68:71], v[88:91], v[52:67]
	ds_read_b128 v[68:71], v1 offset:6720
	s_waitcnt lgkmcnt(0)
	v_mfma_f32_32x32x16_bf16 v[52:67], v[68:71], v[92:95], v[52:67]
	ds_read_b128 v[68:71], v1 offset:6752
	s_waitcnt lgkmcnt(0)
	v_mfma_f32_32x32x16_bf16 v[52:67], v[68:71], v[96:99], v[52:67]
	ds_read_b128 v[68:71], v1 offset:6784
	s_waitcnt lgkmcnt(0)
	v_mfma_f32_32x32x16_bf16 v[52:67], v[68:71], v[100:103], v[52:67]
	ds_read_b128 v[68:71], v1 offset:6816
	s_waitcnt lgkmcnt(0)
	v_mfma_f32_32x32x16_bf16 v[52:67], v[68:71], v[104:107], v[52:67]
	s_cbranch_vccnz .LBB0_1019
; __device__ __forceinline__ int crow(int v, int hi) { return (v & 3) + 8 * (v >> 2) + 4 * hi; }
; template <int D, int DV, int MODE, bool HASBIAS, bool JOINT, bool DEFER, class KA, class VA, class PF, class BF, class VF, class NM, class WS, class CB> ...
;     ...
;             const bool masked = nm(t, 0) || nm(t, 1);
;             if (masked) {
; #pragma unroll
;                 for (int v = 0; v < 16; ++v) { const int kin = crow(v, hi); if (!vf(t, kin)) s0[v] = NEGB; if (!vf(t, 32 + kin)) s1[v] = NEGB; }
;             }
; __device__ __forceinline__ void mla_unit(const KP& P, LAS unsigned char* lds, int b, int h, int qb, int tid_u) {
;     ...
;     auto vf = [&](int t, int kin) -> bool { return 64 * t + kin <= tq; };
;     const int wq_lo = q0 + 32 * w, wq_hi = wq_lo + 31;
;     auto nm = [&](int t, int sub) -> bool { return 64 * t + 32 * sub + 31 > wq_lo; };
.Lmla_m1:
	v_add_u32_e32 v1, s49, v171
	v_add_u32_e32 v68, 0xffffff81, v1
	v_cmp_le_i32_e32 vcc, v68, v134
	v_add_u32_e32 v68, 0xffffffa1, v1
	s_nop 0
	v_cndmask_b32_e32 v36, v239, v36, vcc
	v_cmp_le_i32_e32 vcc, v68, v134
	v_add_u32_e32 v68, 0xffffff82, v1
	s_nop 2
	v_cndmask_b32_e32 v52, v239, v52, vcc
	v_cmp_le_i32_e32 vcc, v68, v134
	v_add_u32_e32 v68, 0xffffffa2, v1
	s_nop 0
	v_cndmask_b32_e32 v37, v239, v37, vcc
	v_cmp_le_i32_e32 vcc, v68, v134
	v_add_u32_e32 v68, 0xffffff83, v1
	s_nop 0
	v_cndmask_b32_e32 v53, v239, v53, vcc
	v_cmp_le_i32_e32 vcc, v68, v134
	v_add_u32_e32 v68, 0xffffffa3, v1
	s_nop 0
	v_cndmask_b32_e32 v38, v239, v38, vcc
	v_cmp_le_i32_e32 vcc, v68, v134
	v_add_u32_e32 v68, 0xffffff84, v1
	s_nop 0
	v_cndmask_b32_e32 v54, v239, v54, vcc
	v_cmp_le_i32_e32 vcc, v68, v134
	v_add_u32_e32 v68, 0xffffffa4, v1
	s_nop 0
	v_cndmask_b32_e32 v39, v239, v39, vcc
	v_cmp_le_i32_e32 vcc, v68, v134
	v_add_u32_e32 v68, 0xffffff89, v1
	s_nop 0
	v_cndmask_b32_e32 v55, v239, v55, vcc
	v_cmp_le_i32_e32 vcc, v68, v134
	v_add_u32_e32 v68, 0xffffffa9, v1
	s_nop 0
	v_cndmask_b32_e32 v40, v239, v40, vcc
	v_cmp_le_i32_e32 vcc, v68, v134
	v_add_u32_e32 v68, 0xffffff8a, v1
	s_nop 0
	v_cndmask_b32_e32 v56, v239, v56, vcc
	v_cmp_le_i32_e32 vcc, v68, v134
	v_add_u32_e32 v68, 0xffffffaa, v1
	s_nop 0
	v_cndmask_b32_e32 v41, v239, v41, vcc
	v_cmp_le_i32_e32 vcc, v68, v134
	v_add_u32_e32 v68, 0xffffff8b, v1
	s_nop 0
	v_cndmask_b32_e32 v57, v239, v57, vcc
	v_cmp_le_i32_e32 vcc, v68, v134
	v_add_u32_e32 v68, 0xffffffab, v1
	s_nop 0
	v_cndmask_b32_e32 v42, v239, v42, vcc
	v_cmp_le_i32_e32 vcc, v68, v134
	v_add_u32_e32 v68, 0xffffff8c, v1
	s_nop 0
	v_cndmask_b32_e32 v58, v239, v58, vcc
	v_cmp_le_i32_e32 vcc, v68, v134
	v_add_u32_e32 v68, 0xffffffac, v1
	s_nop 0
	v_cndmask_b32_e32 v43, v239, v43, vcc
	v_cmp_le_i32_e32 vcc, v68, v134
	v_add_u32_e32 v68, 0xffffff91, v1
	s_nop 0
	v_cndmask_b32_e32 v59, v239, v59, vcc
	v_cmp_le_i32_e32 vcc, v68, v134
	v_add_u32_e32 v68, 0xffffffb1, v1
	s_nop 0
	v_cndmask_b32_e32 v44, v239, v44, vcc
	v_cmp_le_i32_e32 vcc, v68, v134
	v_add_u32_e32 v68, 0xffffff92, v1
	s_nop 0
	v_cndmask_b32_e32 v60, v239, v60, vcc
	v_cmp_le_i32_e32 vcc, v68, v134
	v_add_u32_e32 v68, 0xffffffb2, v1
	s_nop 0
	v_cndmask_b32_e32 v45, v239, v45, vcc
	v_cmp_le_i32_e32 vcc, v68, v134
	v_add_u32_e32 v68, 0xffffff93, v1
	s_nop 0
	v_cndmask_b32_e32 v61, v239, v61, vcc
	v_cmp_le_i32_e32 vcc, v68, v134
	v_add_u32_e32 v68, 0xffffffb3, v1
	s_nop 0
	v_cndmask_b32_e32 v46, v239, v46, vcc
	v_cmp_le_i32_e32 vcc, v68, v134
	v_add_u32_e32 v68, 0xffffff94, v1
	s_nop 0
	v_cndmask_b32_e32 v62, v239, v62, vcc
	v_cmp_le_i32_e32 vcc, v68, v134
	v_add_u32_e32 v68, 0xffffffb4, v1
	s_nop 0
	v_cndmask_b32_e32 v47, v239, v47, vcc
	v_cmp_le_i32_e32 vcc, v68, v134
	v_add_u32_e32 v68, 0xffffff99, v1
	s_nop 0
	v_cndmask_b32_e32 v63, v239, v63, vcc
	v_cmp_le_i32_e32 vcc, v68, v134
	v_add_u32_e32 v68, 0xffffffb9, v1
	s_nop 0
	v_cndmask_b32_e32 v48, v239, v48, vcc
	v_cmp_le_i32_e32 vcc, v68, v134
	v_add_u32_e32 v68, 0xffffff9a, v1
	s_nop 0
	v_cndmask_b32_e32 v64, v239, v64, vcc
	v_cmp_le_i32_e32 vcc, v68, v134
	v_add_u32_e32 v68, 0xffffffba, v1
	s_nop 0
	v_cndmask_b32_e32 v49, v239, v49, vcc
	v_cmp_le_i32_e32 vcc, v68, v134
	v_add_u32_e32 v68, 0xffffff9b, v1
	s_nop 0
	v_cndmask_b32_e32 v65, v239, v65, vcc
	v_cmp_le_i32_e32 vcc, v68, v134
	v_add_u32_e32 v68, 0xffffffbb, v1
	s_nop 0
	v_cndmask_b32_e32 v50, v239, v50, vcc
	v_cmp_le_i32_e32 vcc, v68, v134
	v_add_u32_e32 v68, 0xffffff9c, v1
	v_add_u32_e32 v1, 0xffffffbc, v1
	v_cndmask_b32_e32 v66, v239, v66, vcc
	v_cmp_le_i32_e32 vcc, v68, v134
	s_nop 1
	v_cndmask_b32_e32 v51, v239, v51, vcc
	v_cmp_le_i32_e32 vcc, v1, v134
	s_nop 1
	v_cndmask_b32_e32 v67, v239, v67, vcc

; template <int D, int DV, int MODE, bool HASBIAS, bool JOINT, bool DEFER, class KA, class VA, class PF, class BF, class VF, class NM, class WS, class CB> ...
;     ...
;         if (t + 1 < nt) FA_STORE(t + 1, kregB, vregB, pregB);
.LBB0_1025:
	s_add_i32 s10, s48, -2
	s_cmp_ge_u32 s10, s38
	s_cbranch_scc1 .Lmla_es1_done
	s_and_saveexec_b64 s[10:11], s[40:41]
	s_cbranch_execz .Lmla_es1_a
	v_add_u32_e32 v1, v185, v186
	s_waitcnt vmcnt(0)
	ds_write_b128 v1, v[120:123] offset:13312

; template <int D, int DV, int MODE, bool HASBIAS, bool JOINT, bool DEFER, class KA, class VA, class PF, class BF, class VF, class NM, class WS, class CB> ...
;     ...
;             l += sum0 + sum1; m = mn;
;             if (MODE == 0) {
;                 if (defer_wave) { pp0 = pack8(s0, 0); pp1 = pack8(s0, 1); pp2 = pack8(s1, 0); pp3 = pack8(s1, 1); pend = vslot; }
;                 else { pv_sub<DV / 32>(o, curv, VS, 0, s0, r32, hi); pv_sub<DV / 32>(o, curv, VS, 1, s1, r32, hi); }
;     ...
;         if (t + 1 < nt) FA_STORE(t + 1, kregB, vregB, pregB);
;         __syncthreads();
.Lmla_es1_done:
	v_add_u32_e32 v1, v175, v184
	v_cvt_pk_bf16_f32 v194, v151, v157
	v_cvt_pk_bf16_f32 v195, v153, v161
	ds_read_b128 v[198:201], v1 offset:26624
	ds_read_b128 v[48:51], v1 offset:31232
	v_cvt_pk_bf16_f32 v196, v155, v165
	v_cvt_pk_bf16_f32 v197, v159, v167
	s_mov_b64 s[10:11], 0
	v_add_f32_e32 v168, 0, v150
	v_add_f32_e32 v169, 0, v151
	v_cvt_pk_bf16_f32 v36, v69, v75
	v_add_f32_e32 v168, v156, v168
	v_add_f32_e32 v169, v157, v169
	s_waitcnt lgkmcnt(1)
	v_mfma_f32_32x32x16_bf16 v[4:19], v[198:201], v[194:197], v[4:19]
	ds_read_b128 v[52:55], v1 offset:26656
	ds_read_b128 v[56:59], v1 offset:31264
	v_cvt_pk_bf16_f32 v37, v71, v79
	v_add_f32_e32 v168, v152, v168
	v_add_f32_e32 v169, v153, v169
	v_cvt_pk_bf16_f32 v38, v73, v81
	v_add_f32_e32 v168, v160, v168
	v_add_f32_e32 v169, v161, v169
	s_waitcnt lgkmcnt(2)
	v_mfma_f32_32x32x16_bf16 v[20:35], v[48:51], v[194:197], v[20:35]
	v_cvt_pk_bf16_f32 v39, v77, v83
	v_add_f32_e32 v168, v154, v168
	v_add_f32_e32 v169, v155, v169
	v_cvt_pk_bf16_f32 v40, v150, v156
	v_add_f32_e32 v168, v164, v168
	v_add_f32_e32 v169, v165, v169
	s_waitcnt lgkmcnt(1)
	v_mfma_f32_32x32x16_bf16 v[4:19], v[52:55], v[36:39], v[4:19]
	ds_read_b128 v[60:63], v1 offset:26688
	ds_read_b128 v[64:67], v1 offset:31296
	v_cvt_pk_bf16_f32 v41, v152, v160
	v_add_f32_e32 v168, v158, v168
	v_add_f32_e32 v169, v159, v169
	v_cvt_pk_bf16_f32 v42, v154, v164
	v_add_f32_e32 v168, v166, v168
	v_add_f32_e32 v169, v167, v169
	s_waitcnt lgkmcnt(2)
	v_mfma_f32_32x32x16_bf16 v[20:35], v[56:59], v[36:39], v[20:35]
	v_cvt_pk_bf16_f32 v43, v158, v166
	v_add_f32_e32 v168, v68, v168
	v_add_f32_e32 v169, v69, v169
	v_cvt_pk_bf16_f32 v44, v68, v74
	v_add_f32_e32 v168, v74, v168
	v_add_f32_e32 v169, v75, v169
	s_waitcnt lgkmcnt(1)
	v_mfma_f32_32x32x16_bf16 v[4:19], v[60:63], v[40:43], v[4:19]
	ds_read_b128 v[198:201], v1 offset:26720
	ds_read_b128 v[48:51], v1 offset:31328
	v_cvt_pk_bf16_f32 v45, v70, v78
	v_add_f32_e32 v168, v70, v168
	v_add_f32_e32 v169, v71, v169
	v_cvt_pk_bf16_f32 v46, v72, v80
	v_add_f32_e32 v168, v78, v168
	v_add_f32_e32 v169, v79, v169
	s_waitcnt lgkmcnt(2)
	v_mfma_f32_32x32x16_bf16 v[20:35], v[64:67], v[40:43], v[20:35]
	v_cvt_pk_bf16_f32 v47, v76, v82
	v_add_f32_e32 v168, v72, v168
	v_add_f32_e32 v169, v73, v169
	v_add_f32_e32 v168, v80, v168
	v_add_f32_e32 v169, v81, v169
	s_waitcnt lgkmcnt(1)
	v_mfma_f32_32x32x16_bf16 v[4:19], v[198:201], v[44:47], v[4:19]
	v_add_f32_e32 v168, v76, v168
	v_add_f32_e32 v169, v77, v169
	v_add_f32_e32 v168, v82, v168
	v_add_f32_e32 v169, v83, v169
	s_waitcnt lgkmcnt(0)
	v_mfma_f32_32x32x16_bf16 v[20:35], v[48:51], v[44:47], v[20:35]
	v_add_f32_e32 v168, v168, v169
	v_add_f32_e32 v192, v168, v192
	s_add_i32 s10, s48, -2
	s_cmp_lt_u32 s10, s38
	s_cselect_b64 s[8:9], -1, 0
	s_branch .LBB0_1057

; template <int D, int DV, int MODE, bool HASBIAS, bool JOINT, bool DEFER, class KA, class VA, class PF, class BF, class VF, class NM, class WS, class CB> ...
;     ...
;         __syncthreads();
;         if (t + 1 < nt) {
;             if (t + 3 < nt) FA_LOAD(t + 3, kregB, vregB, pregB);
.LBB0_1057:
	s_andn2_b64 vcc, exec, s[8:9]
	s_waitcnt lgkmcnt(0)
	s_barrier
	s_cbranch_vccnz .LBB0_1083
	s_sub_i32 s10, s49, 63
	s_sub_i32 s11, s49, 31
	s_max_i32 s10, s10, s11
	s_cmp_gt_i32 s10, s39
	s_cbranch_scc0 .LBB0_1072
	s_cmp_ge_u32 s48, s38
	s_cbranch_scc1 .LBB0_1072
	s_lshl_b32 s8, s54, 6
	s_add_i32 s74, s8, 0xc0
	s_and_saveexec_b64 s[8:9], s[40:41]
	s_cbranch_execz .LBB0_1065
	s_and_saveexec_b64 s[10:11], s[44:45]
	s_xor_b64 s[10:11], exec, s[10:11]
	v_lshl_add_u64 v[36:37], v[136:137], 0, s[74:75]
	v_lshlrev_b64 v[36:37], 6, v[36:37]
	v_lshl_add_u64 v[36:37], v[140:141], 0, v[36:37]
	s_mov_b64 s[12:13], 0x340fff80
	v_lshl_add_u64 v[36:37], v[36:37], 0, s[12:13]
	s_andn2_saveexec_b64 s[10:11], s[10:11]
	v_lshl_add_u64 v[36:37], s[20:21], 0, v[146:147]
	s_mov_b64 s[12:13], 0x24130000
	v_lshl_add_u64 v[36:37], v[36:37], 0, s[12:13]
	s_or_b64 exec, exec, s[10:11]
	global_load_dwordx4 v[120:123], v[36:37], off

; #define LAS __attribute__((address_space(3)))
; template <int DK16>
; __device__ __forceinline__ f32x16 qk_sub(const LAS unsigned char* Kt, int ks, int sub, const bf16x8 (&qf)[DK16], int r32, int hi) {
;     f32x16 s;
; #pragma unroll
;     for (int v = 0; v < 16; ++v) s[v] = 0.f;
;     const LAS unsigned char* p = Kt + (sub * 32 + r32) * ks + hi * 16;
; #pragma unroll
;     for (int dk = 0; dk < DK16; ++dk) { const bf16x8 kf = *(const LAS bf16x8*)(p + dk * 32); s = __builtin_amdgcn_mfma_f32_32x32x16_bf16(kf, qf[dk], s, 0, 0, 0); }
;     return s;
; }
.LBB0_1072:
	s_sub_i32 s10, s49, 63
	s_cmp_le_i32 s10, s39
	s_cselect_b64 s[8:9], -1, 0
	s_sub_i32 s11, s49, 31
	s_cmp_le_i32 s11, s39
	s_cselect_b64 s[18:19], -1, 0
	s_max_i32 s10, s10, s11
	s_cmp_gt_i32 s10, s39
	s_cselect_b64 s[10:11], -1, 0
	s_andn2_b64 vcc, exec, s[10:11]
	s_cbranch_vccz .LBB0_1084
	v_add_u32_e32 v1, v173, v2
	ds_read_b128 v[36:39], v1 offset:13312
	ds_read_b128 v[52:55], v1 offset:13344
	s_cmp_ge_u32 s48, s38
	s_cbranch_scc1 .Lmla_qkp2
	s_lshl_b32 s74, s54, 6
	s_add_i32 s74, s74, 0xc0
	s_mov_b64 s[12:13], 0x340fff80
	s_mov_b64 s[100:101], 0x24130000
	s_sub_i32 s10, s49, 32
	s_max_i32 s10, s10, s49
	s_cmp_le_i32 s10, s30
	s_cselect_b64 s[16:17], -1, 0
	s_and_b64 vcc, exec, s[16:17]
	s_waitcnt lgkmcnt(0)
	v_mfma_f32_32x32x16_bf16 v[36:51], v[36:39], v[84:87], 0
	ds_read_b128 v[68:71], v1 offset:20000
	v_lshl_add_u64 v[72:73], v[136:137], 0, s[74:75]
	v_lshlrev_b64 v[72:73], 6, v[72:73]
	v_lshl_add_u64 v[72:73], v[140:141], 0, v[72:73]
	v_lshl_add_u64 v[72:73], v[72:73], 0, s[12:13]
	v_mfma_f32_32x32x16_bf16 v[36:51], v[52:55], v[88:91], v[36:51]
	ds_read_b128 v[52:55], v1 offset:13376
	v_lshl_add_u64 v[74:75], s[20:21], 0, v[146:147]
	v_lshl_add_u64 v[74:75], v[74:75], 0, s[100:101]
	v_cndmask_b32_e64 v72, v74, v72, s[44:45]
	v_cndmask_b32_e64 v73, v75, v73, s[44:45]
	s_waitcnt lgkmcnt(0)
	v_mfma_f32_32x32x16_bf16 v[36:51], v[52:55], v[92:95], v[36:51]
	global_load_dwordx4 v[120:123], v[72:73], off
	ds_read_b128 v[52:55], v1 offset:13408
	v_lshl_add_u64 v[72:73], v[138:139], 0, s[74:75]
	v_lshlrev_b64 v[72:73], 6, v[72:73]
	v_lshl_add_u64 v[72:73], v[142:143], 0, v[72:73]
	v_lshl_add_u64 v[72:73], v[72:73], 0, s[12:13]
	s_waitcnt lgkmcnt(0)
	v_mfma_f32_32x32x16_bf16 v[36:51], v[52:55], v[96:99], v[36:51]
	ds_read_b128 v[52:55], v1 offset:13440
	v_lshl_add_u64 v[74:75], s[20:21], 0, v[148:149]
	v_lshl_add_u64 v[74:75], v[74:75], 0, s[100:101]
	v_cndmask_b32_e64 v72, v74, v72, s[46:47]
	v_cndmask_b32_e64 v73, v75, v73, s[46:47]
	s_waitcnt lgkmcnt(0)
	v_mfma_f32_32x32x16_bf16 v[36:51], v[52:55], v[100:103], v[36:51]
	ds_read_b128 v[52:55], v1 offset:13472
	s_cmp_eq_u64 s[42:43], 0
	s_cbranch_scc1 .Lmla_c2s2
	global_load_dwordx4 v[124:127], v[72:73], off
.Lmla_c2s2:
	v_lshl_add_u64 v[74:75], s[20:21], 0, v[144:145]
	s_mov_b64 s[12:13], 0x28100000
	v_lshl_add_u64 v[74:75], v[74:75], 0, s[12:13]
	s_waitcnt lgkmcnt(0)
	v_mfma_f32_32x32x16_bf16 v[36:51], v[52:55], v[104:107], v[36:51]
	global_load_dwordx4 v[128:131], v[74:75], off offset:384
	ds_read_b128 v[52:55], v1 offset:19968
	s_waitcnt lgkmcnt(0)
	v_mfma_f32_32x32x16_bf16 v[52:67], v[52:55], v[84:87], 0
	v_mfma_f32_32x32x16_bf16 v[52:67], v[68:71], v[88:91], v[52:67]
	ds_read_b128 v[68:71], v1 offset:20032
	s_waitcnt lgkmcnt(0)
	v_mfma_f32_32x32x16_bf16 v[52:67], v[68:71], v[92:95], v[52:67]
	ds_read_b128 v[68:71], v1 offset:20064
	s_waitcnt lgkmcnt(0)
	v_mfma_f32_32x32x16_bf16 v[52:67], v[68:71], v[96:99], v[52:67]
	ds_read_b128 v[68:71], v1 offset:20096
	s_waitcnt lgkmcnt(0)
	v_mfma_f32_32x32x16_bf16 v[52:67], v[68:71], v[100:103], v[52:67]
	ds_read_b128 v[68:71], v1 offset:20128
	s_waitcnt lgkmcnt(0)
	v_mfma_f32_32x32x16_bf16 v[52:67], v[68:71], v[104:107], v[52:67]
	s_cbranch_vccnz .LBB0_1075
	s_branch .Lmla_m2
.Lmla_qkp2:
	s_sub_i32 s10, s49, 32
	s_max_i32 s10, s10, s49
	s_cmp_le_i32 s10, s30
	s_waitcnt lgkmcnt(0)
	v_mfma_f32_32x32x16_bf16 v[36:51], v[36:39], v[84:87], 0
	s_cselect_b64 s[16:17], -1, 0
	s_and_b64 vcc, exec, s[16:17]
	ds_read_b128 v[68:71], v1 offset:20000
	v_mfma_f32_32x32x16_bf16 v[36:51], v[52:55], v[88:91], v[36:51]
	ds_read_b128 v[52:55], v1 offset:13376
	s_waitcnt lgkmcnt(0)
	v_mfma_f32_32x32x16_bf16 v[36:51], v[52:55], v[92:95], v[36:51]
	ds_read_b128 v[52:55], v1 offset:13408
	s_waitcnt lgkmcnt(0)
	v_mfma_f32_32x32x16_bf16 v[36:51], v[52:55], v[96:99], v[36:51]
	ds_read_b128 v[52:55], v1 offset:13440
	s_waitcnt lgkmcnt(0)
	v_mfma_f32_32x32x16_bf16 v[36:51], v[52:55], v[100:103], v[36:51]
	ds_read_b128 v[52:55], v1 offset:13472
	s_waitcnt lgkmcnt(0)
	v_mfma_f32_32x32x16_bf16 v[36:51], v[52:55], v[104:107], v[36:51]
	ds_read_b128 v[52:55], v1 offset:19968
	s_waitcnt lgkmcnt(0)
	v_mfma_f32_32x32x16_bf16 v[52:67], v[52:55], v[84:87], 0
	v_mfma_f32_32x32x16_bf16 v[52:67], v[68:71], v[88:91], v[52:67]
	ds_read_b128 v[68:71], v1 offset:20032
	s_waitcnt lgkmcnt(0)
	v_mfma_f32_32x32x16_bf16 v[52:67], v[68:71], v[92:95], v[52:67]
	ds_read_b128 v[68:71], v1 offset:20064
	s_waitcnt lgkmcnt(0)
	v_mfma_f32_32x32x16_bf16 v[52:67], v[68:71], v[96:99], v[52:67]
	ds_read_b128 v[68:71], v1 offset:20096
	s_waitcnt lgkmcnt(0)
	v_mfma_f32_32x32x16_bf16 v[52:67], v[68:71], v[100:103], v[52:67]
	ds_read_b128 v[68:71], v1 offset:20128
	s_waitcnt lgkmcnt(0)
	v_mfma_f32_32x32x16_bf16 v[52:67], v[68:71], v[104:107], v[52:67]
	s_cbranch_vccnz .LBB0_1075
; __device__ __forceinline__ int crow(int v, int hi) { return (v & 3) + 8 * (v >> 2) + 4 * hi; }
; template <int D, int DV, int MODE, bool HASBIAS, bool JOINT, bool DEFER, class KA, class VA, class PF, class BF, class VF, class NM, class WS, class CB> ...
;     ...
;             const bool masked = nm(t, 0) || nm(t, 1);
;             if (masked) {
; #pragma unroll
;                 for (int v = 0; v < 16; ++v) { const int kin = crow(v, hi); if (!vf(t, kin)) s0[v] = NEGB; if (!vf(t, 32 + kin)) s1[v] = NEGB; }
;             }
; __device__ __forceinline__ void mla_unit(const KP& P, LAS unsigned char* lds, int b, int h, int qb, int tid_u) {
;     ...
;     auto vf = [&](int t, int kin) -> bool { return 64 * t + kin <= tq; };
;     const int wq_lo = q0 + 32 * w, wq_hi = wq_lo + 31;
;     auto nm = [&](int t, int sub) -> bool { return 64 * t + 32 * sub + 31 > wq_lo; };
.Lmla_m2:
	v_add_u32_e32 v1, s49, v171
	v_subrev_u32_e32 v68, 63, v1
	v_cmp_le_i32_e32 vcc, v68, v134
	v_subrev_u32_e32 v68, 31, v1
	s_nop 0
	v_cndmask_b32_e32 v36, v239, v36, vcc
	v_cmp_le_i32_e32 vcc, v68, v134
	v_subrev_u32_e32 v68, 62, v1
	s_nop 2
	v_cndmask_b32_e32 v52, v239, v52, vcc
	v_cmp_le_i32_e32 vcc, v68, v134
	v_subrev_u32_e32 v68, 30, v1
	s_nop 0
	v_cndmask_b32_e32 v37, v239, v37, vcc
	v_cmp_le_i32_e32 vcc, v68, v134
	v_subrev_u32_e32 v68, 61, v1
	s_nop 0
	v_cndmask_b32_e32 v53, v239, v53, vcc
	v_cmp_le_i32_e32 vcc, v68, v134
	v_subrev_u32_e32 v68, 29, v1
	s_nop 0
	v_cndmask_b32_e32 v38, v239, v38, vcc
	v_cmp_le_i32_e32 vcc, v68, v134
	v_subrev_u32_e32 v68, 60, v1
	s_nop 0
	v_cndmask_b32_e32 v54, v239, v54, vcc
	v_cmp_le_i32_e32 vcc, v68, v134
	v_subrev_u32_e32 v68, 28, v1
	s_nop 0
	v_cndmask_b32_e32 v39, v239, v39, vcc
	v_cmp_le_i32_e32 vcc, v68, v134
	v_subrev_u32_e32 v68, 55, v1
	s_nop 0
	v_cndmask_b32_e32 v55, v239, v55, vcc
	v_cmp_le_i32_e32 vcc, v68, v134
	v_subrev_u32_e32 v68, 23, v1
	s_nop 0
	v_cndmask_b32_e32 v40, v239, v40, vcc
	v_cmp_le_i32_e32 vcc, v68, v134
	v_subrev_u32_e32 v68, 54, v1
	s_nop 0
	v_cndmask_b32_e32 v56, v239, v56, vcc
	v_cmp_le_i32_e32 vcc, v68, v134
	v_subrev_u32_e32 v68, 22, v1
	s_nop 0
	v_cndmask_b32_e32 v41, v239, v41, vcc
	v_cmp_le_i32_e32 vcc, v68, v134
	v_subrev_u32_e32 v68, 53, v1
	s_nop 0
	v_cndmask_b32_e32 v57, v239, v57, vcc
	v_cmp_le_i32_e32 vcc, v68, v134
	v_subrev_u32_e32 v68, 21, v1
	s_nop 0
	v_cndmask_b32_e32 v42, v239, v42, vcc
	v_cmp_le_i32_e32 vcc, v68, v134
	v_subrev_u32_e32 v68, 52, v1
	s_nop 0
	v_cndmask_b32_e32 v58, v239, v58, vcc
	v_cmp_le_i32_e32 vcc, v68, v134
	v_subrev_u32_e32 v68, 20, v1
	s_nop 0
	v_cndmask_b32_e32 v43, v239, v43, vcc
	v_cmp_le_i32_e32 vcc, v68, v134
	v_subrev_u32_e32 v68, 47, v1
	s_nop 0
	v_cndmask_b32_e32 v59, v239, v59, vcc
	v_cmp_le_i32_e32 vcc, v68, v134
	v_add_u32_e32 v68, -15, v1
	s_nop 0
	v_cndmask_b32_e32 v44, v239, v44, vcc
	v_cmp_le_i32_e32 vcc, v68, v134
	v_subrev_u32_e32 v68, 46, v1
	s_nop 0
	v_cndmask_b32_e32 v60, v239, v60, vcc
	v_cmp_le_i32_e32 vcc, v68, v134
	v_add_u32_e32 v68, -14, v1
	s_nop 0
	v_cndmask_b32_e32 v45, v239, v45, vcc
	v_cmp_le_i32_e32 vcc, v68, v134
	v_subrev_u32_e32 v68, 45, v1
	s_nop 0
	v_cndmask_b32_e32 v61, v239, v61, vcc
	v_cmp_le_i32_e32 vcc, v68, v134
	v_add_u32_e32 v68, -13, v1
	s_nop 0
	v_cndmask_b32_e32 v46, v239, v46, vcc
	v_cmp_le_i32_e32 vcc, v68, v134
	v_subrev_u32_e32 v68, 44, v1
	s_nop 0
	v_cndmask_b32_e32 v62, v239, v62, vcc
	v_cmp_le_i32_e32 vcc, v68, v134
	v_add_u32_e32 v68, -12, v1
	s_nop 0
	v_cndmask_b32_e32 v47, v239, v47, vcc
	v_cmp_le_i32_e32 vcc, v68, v134
	v_subrev_u32_e32 v68, 39, v1
	s_nop 0
	v_cndmask_b32_e32 v63, v239, v63, vcc
	v_cmp_le_i32_e32 vcc, v68, v134
	v_add_u32_e32 v68, -7, v1
	s_nop 0
	v_cndmask_b32_e32 v48, v239, v48, vcc
	v_cmp_le_i32_e32 vcc, v68, v134
	v_subrev_u32_e32 v68, 38, v1
	s_nop 0
	v_cndmask_b32_e32 v64, v239, v64, vcc
	v_cmp_le_i32_e32 vcc, v68, v134
	v_add_u32_e32 v68, -6, v1
	s_nop 0
	v_cndmask_b32_e32 v49, v239, v49, vcc
	v_cmp_le_i32_e32 vcc, v68, v134
	v_subrev_u32_e32 v68, 37, v1
	s_nop 0
	v_cndmask_b32_e32 v65, v239, v65, vcc
	v_cmp_le_i32_e32 vcc, v68, v134
	v_add_u32_e32 v68, -5, v1
	s_nop 0
	v_cndmask_b32_e32 v50, v239, v50, vcc
	v_cmp_le_i32_e32 vcc, v68, v134
	v_subrev_u32_e32 v68, 36, v1
	v_add_u32_e32 v1, -4, v1
	v_cndmask_b32_e32 v66, v239, v66, vcc
	v_cmp_le_i32_e32 vcc, v68, v134
	s_nop 1
	v_cndmask_b32_e32 v51, v239, v51, vcc
	v_cmp_le_i32_e32 vcc, v1, v134
	s_nop 1
	v_cndmask_b32_e32 v67, v239, v67, vcc

; template <int D, int DV, int MODE, bool HASBIAS, bool JOINT, bool DEFER, class KA, class VA, class PF, class BF, class VF, class NM, class WS, class CB> ...
;     ...
;             l += sum0 + sum1; m = mn;
;             if (MODE == 0) {
;                 if (defer_wave) { pp0 = pack8(s0, 0); pp1 = pack8(s0, 1); pp2 = pack8(s1, 0); pp3 = pack8(s1, 1); pend = vslot; }
;                 else { pv_sub<DV / 32>(o, curv, VS, 0, s0, r32, hi); pv_sub<DV / 32>(o, curv, VS, 1, s1, r32, hi); }
.LBB0_1081:
	s_cmp_eq_u64 s[0:1], 0
	s_cbranch_scc1 .Lmla_es2_done
	s_and_saveexec_b64 s[10:11], s[40:41]
	s_cbranch_execz .Lmla_es2_a
	v_add_u32_e32 v1, v185, v186
	s_waitcnt vmcnt(0)
	ds_write_b128 v1, v[108:111]
.Lmla_es2_a:
	s_or_b64 exec, exec, s[10:11]
	s_and_saveexec_b64 s[10:11], s[42:43]
	s_cbranch_execz .Lmla_es2_b
	v_add_u32_e32 v1, v187, v188
	s_waitcnt vmcnt(0)
	ds_write_b128 v1, v[112:115]
.Lmla_es2_b:
	s_or_b64 exec, exec, s[10:11]
	s_waitcnt vmcnt(0)
	ds_write2_b64 v170, v[116:117], v[118:119] offset1:2
.Lmla_es2_done:
	v_add_u32_e32 v1, v175, v184
	v_cvt_pk_bf16_f32 v194, v151, v157
	v_cvt_pk_bf16_f32 v195, v153, v161
	ds_read_b128 v[198:201], v1 offset:35840
	ds_read_b128 v[48:51], v1 offset:40448
	v_cvt_pk_bf16_f32 v196, v155, v165
	v_cvt_pk_bf16_f32 v197, v159, v167
	s_mov_b64 s[10:11], 0
	v_add_f32_e32 v168, 0, v150
	v_add_f32_e32 v169, 0, v151
	v_cvt_pk_bf16_f32 v36, v69, v75
	v_add_f32_e32 v168, v156, v168
	v_add_f32_e32 v169, v157, v169
	s_waitcnt lgkmcnt(1)
	v_mfma_f32_32x32x16_bf16 v[4:19], v[198:201], v[194:197], v[4:19]
	ds_read_b128 v[52:55], v1 offset:35872
	ds_read_b128 v[56:59], v1 offset:40480
	v_cvt_pk_bf16_f32 v37, v71, v79
	v_add_f32_e32 v168, v152, v168
	v_add_f32_e32 v169, v153, v169
	v_cvt_pk_bf16_f32 v38, v73, v81
	v_add_f32_e32 v168, v160, v168
	v_add_f32_e32 v169, v161, v169
	s_waitcnt lgkmcnt(2)
	v_mfma_f32_32x32x16_bf16 v[20:35], v[48:51], v[194:197], v[20:35]
	v_cvt_pk_bf16_f32 v39, v77, v83
	v_add_f32_e32 v168, v154, v168
	v_add_f32_e32 v169, v155, v169
	v_cvt_pk_bf16_f32 v40, v150, v156
	v_add_f32_e32 v168, v164, v168
	v_add_f32_e32 v169, v165, v169
	s_waitcnt lgkmcnt(1)
	v_mfma_f32_32x32x16_bf16 v[4:19], v[52:55], v[36:39], v[4:19]
	ds_read_b128 v[60:63], v1 offset:35904
	ds_read_b128 v[64:67], v1 offset:40512
	v_cvt_pk_bf16_f32 v41, v152, v160
	v_add_f32_e32 v168, v158, v168
	v_add_f32_e32 v169, v159, v169
	v_cvt_pk_bf16_f32 v42, v154, v164
	v_add_f32_e32 v168, v166, v168
	v_add_f32_e32 v169, v167, v169
	s_waitcnt lgkmcnt(2)
	v_mfma_f32_32x32x16_bf16 v[20:35], v[56:59], v[36:39], v[20:35]
	v_cvt_pk_bf16_f32 v43, v158, v166
	v_add_f32_e32 v168, v68, v168
	v_add_f32_e32 v169, v69, v169
	v_cvt_pk_bf16_f32 v44, v68, v74
	v_add_f32_e32 v168, v74, v168
	v_add_f32_e32 v169, v75, v169
	s_waitcnt lgkmcnt(1)
	v_mfma_f32_32x32x16_bf16 v[4:19], v[60:63], v[40:43], v[4:19]
	ds_read_b128 v[198:201], v1 offset:35936
	ds_read_b128 v[48:51], v1 offset:40544
	v_cvt_pk_bf16_f32 v45, v70, v78
	v_add_f32_e32 v168, v70, v168
	v_add_f32_e32 v169, v71, v169
	v_cvt_pk_bf16_f32 v46, v72, v80
	v_add_f32_e32 v168, v78, v168
	v_add_f32_e32 v169, v79, v169
	s_waitcnt lgkmcnt(2)
	v_mfma_f32_32x32x16_bf16 v[20:35], v[64:67], v[40:43], v[20:35]
	v_cvt_pk_bf16_f32 v47, v76, v82
	v_add_f32_e32 v168, v72, v168
	v_add_f32_e32 v169, v73, v169
	v_add_f32_e32 v168, v80, v168
	v_add_f32_e32 v169, v81, v169
	s_waitcnt lgkmcnt(1)
	v_mfma_f32_32x32x16_bf16 v[4:19], v[198:201], v[44:47], v[4:19]
	v_add_f32_e32 v168, v76, v168
	v_add_f32_e32 v169, v77, v169
	v_add_f32_e32 v168, v82, v168
	v_add_f32_e32 v169, v83, v169
	s_waitcnt lgkmcnt(0)
	v_mfma_f32_32x32x16_bf16 v[20:35], v[48:51], v[44:47], v[20:35]
	v_add_f32_e32 v168, v168, v169
	v_add_f32_e32 v191, v168, v191
	s_branch .LBB0_1114

; #define LAS __attribute__((address_space(3)))
; __global__ void __launch_bounds__(512, 2) mega(Args a) {
;     extern __shared__ __attribute__((aligned(16))) unsigned char lds_raw[];
;     LAS unsigned char* lds = (LAS unsigned char*)lds_raw;
;     cg::grid_group grid = cg::this_grid();
;     const int wv = __builtin_amdgcn_readfirstlane((int)threadIdx.x >> 6);
;     const int G = gridDim.x, gw = blockIdx.x * 8 + wv, NGW = G * 8;
	.amdhsa_kernel _Z4mega4Args
		.amdhsa_group_segment_fixed_size 0
		.amdhsa_private_segment_fixed_size 0
		.amdhsa_kernarg_size 504
		.amdhsa_user_sgpr_count 2
		.amdhsa_user_sgpr_dispatch_ptr 0
		.amdhsa_user_sgpr_queue_ptr 0
		.amdhsa_user_sgpr_kernarg_segment_ptr 1
		.amdhsa_user_sgpr_dispatch_id 0
		.amdhsa_user_sgpr_kernarg_preload_length 0
		.amdhsa_user_sgpr_kernarg_preload_offset 0
		.amdhsa_user_sgpr_private_segment_size 0
		.amdhsa_uses_dynamic_stack 0
		.amdhsa_enable_private_segment 0
		.amdhsa_system_sgpr_workgroup_id_x 1
		.amdhsa_system_sgpr_workgroup_id_y 0
		.amdhsa_system_sgpr_workgroup_id_z 0
		.amdhsa_system_sgpr_workgroup_info 0
		.amdhsa_system_vgpr_workitem_id 0
		.amdhsa_next_free_vgpr 256
		.amdhsa_next_free_sgpr 102
		.amdhsa_accum_offset 256
		.amdhsa_reserve_vcc 1
		.amdhsa_float_round_mode_32 0
		.amdhsa_float_round_mode_16_64 0
		.amdhsa_float_denorm_mode_32 3
		.amdhsa_float_denorm_mode_16_64 3
		.amdhsa_dx10_clamp 1
		.amdhsa_ieee_mode 1
		.amdhsa_fp16_overflow 0
		.amdhsa_tg_split 0
		.amdhsa_exception_fp_ieee_invalid_op 0
		.amdhsa_exception_fp_denorm_src 0
		.amdhsa_exception_fp_ieee_div_zero 0
		.amdhsa_exception_fp_ieee_overflow 0
		.amdhsa_exception_fp_ieee_underflow 0
		.amdhsa_exception_fp_ieee_inexact 0
		.amdhsa_exception_int_div_zero 0
	.end_amdhsa_kernel

; #define LAS __attribute__((address_space(3)))
; __global__ void __launch_bounds__(512, 2) mega(Args a) {
;     extern __shared__ __attribute__((aligned(16))) unsigned char lds_raw[];
;     LAS unsigned char* lds = (LAS unsigned char*)lds_raw;
;     cg::grid_group grid = cg::this_grid();
;     const int wv = __builtin_amdgcn_readfirstlane((int)threadIdx.x >> 6);
;     const int G = gridDim.x, gw = blockIdx.x * 8 + wv, NGW = G * 8;
amdhsa.kernels:
  - .agpr_count:     0
    .args:
      - .offset:         0
        .size:           248
        .value_kind:     by_value
      - .offset:         248
        .size:           4
        .value_kind:     hidden_block_count_x
      - .offset:         252
        .size:           4
        .value_kind:     hidden_block_count_y
      - .offset:         256
        .size:           4
        .value_kind:     hidden_block_count_z
      - .offset:         260
        .size:           2
        .value_kind:     hidden_group_size_x
      - .offset:         262
        .size:           2
        .value_kind:     hidden_group_size_y
      - .offset:         264
        .size:           2
        .value_kind:     hidden_group_size_z
      - .offset:         266
        .size:           2
        .value_kind:     hidden_remainder_x
      - .offset:         268
        .size:           2
        .value_kind:     hidden_remainder_y
      - .offset:         270
        .size:           2
        .value_kind:     hidden_remainder_z
      - .offset:         288
        .size:           8
        .value_kind:     hidden_global_offset_x
      - .offset:         296
        .size:           8
        .value_kind:     hidden_global_offset_y
      - .offset:         304
        .size:           8
        .value_kind:     hidden_global_offset_z
      - .offset:         312
        .size:           2
        .value_kind:     hidden_grid_dims
      - .offset:         368
        .size:           4
        .value_kind:     hidden_dynamic_lds_size
    .group_segment_fixed_size: 0
    .kernarg_segment_align: 8
    .kernarg_segment_size: 504
    .language:       OpenCL C
    .language_version:
      - 2
      - 0
    .max_flat_workgroup_size: 512
    .name:           _Z4mega4Args
    .private_segment_fixed_size: 0
    .sgpr_count:     108
    .sgpr_spill_count: 297
    .symbol:         _Z4mega4Args.kd
    .uniform_work_group_size: 1
    .uses_dynamic_stack: false
    .vgpr_count:     256
    .vgpr_spill_count: 0
    .wavefront_size: 64
